# ADIFF: 4-slot KV ring + per-wave fast path without the reference-point (kone) MFMAs when m<60 (softmax shift-invariant), original loop kept as fallback
# baseline (speedup 1.0000x reference)
; #define LAS __attribute__((address_space(3)))
; __device__ __forceinline__ unsigned pk_bf16(float lo, float hi) { const f32x2 v = {lo, hi}; const bf16v2 b = __builtin_convertvector(v, bf16v2); return __builtin_bit_cast(unsigned, b); }
; __device__ __forceinline__ void diff_attn_phase(const Params& p, LAS unsigned char* lds) {
;     ...
;         { const float kmx = __uint_as_float(((const unsigned*)(p.ws + WS_KMAX))[b * 16 + h * 2 + comp]);
; #pragma unroll
;           for (int r = 0; r < 2; ++r) { float s = 0.f;
; #pragma unroll
;               for (int ks = 0; ks < 4; ++ks) { const u32x4 qv = __builtin_bit_cast(u32x4, qf[r][ks]);
; #pragma unroll
;                   for (int i = 0; i < 4; ++i) { const float x0 = bf_lo(qv[i]), x1 = bf_hi(qv[i]); s += x0 * x0 + x1 * x1; } }
;               m[r] = sqrtf(xsum32(s) * kmx) * 1.001f + 1e-3f; } }
;         bf16x8 kone, qm[2];
;         { const unsigned one = hh == 0 ? 0x3F80u : 0u; kone = __builtin_bit_cast(bf16x8, (u32x4){one, 0u, 0u, 0u});
; #pragma unroll
;           for (int r = 0; r < 2; ++r) { const unsigned mb = hh == 0 ? (pk_bf16(-m[r], 0.f) & 0xffffu) : 0u; qm[r] = __builtin_bit_cast(bf16x8, (u32x4){mb, 0u, 0u, 0u}); } }
;         auto issue = [&](int ch, int stg) {
;             const char* kg = (const char*)(kp + (tokb + 64 * ch) * ld); const char* vg = (const char*)(vp + (tokb + 64 * ch) * ld);
;             LAS unsigned char* sb = lds + stg * STG;
; #pragma unroll
;             for (int i = 0; i < 2; ++i) { unsigned o = doff[i]; asm volatile("" : "+v"(o));
;                 __builtin_amdgcn_global_load_lds((const void*)(kg + o), (LAS void*)(sb + dlds[i]), 16, 0, 0);
;                 __builtin_amdgcn_global_load_lds((const void*)(vg + o), (LAS void*)(sb + 16384 + dlds[i]), 16, 0, 0); }
;         };
;         issue(0, 0); issue(1, 1);
;         int s_cur = 0, s_nn = 2;
;         for (int ch = 0; ch < NCH; ++ch) {
;             if (ch + 1 < NCH) asm volatile("s_waitcnt vmcnt(4)" ::: "memory"); else asm volatile("s_waitcnt vmcnt(0)" ::: "memory");
;             __builtin_amdgcn_s_barrier(); asm volatile("" ::: "memory");
;             if (ch + 2 < NCH) issue(ch + 2, s_nn);
;             const LAS unsigned char* Ksb = lds + s_cur * STG; const LAS unsigned char* Vsb = Ksb + 16384;
;             s_nn = s_cur; s_cur = (s_cur == 2) ? 0 : s_cur + 1;
.LBB0_40:
	s_or_b64 exec, exec, s[52:53]
	s_lshl_b32 s2, s5, 7
	s_lshl_b32 s5, s2, 1
	s_add_u32 s22, s36, s5
	s_addc_u32 s23, s70, 0
	s_add_u32 s25, s78, s5
	s_addc_u32 s28, s83, 0
	s_lshl_b64 s[10:11], s[46:47], 26
	s_add_u32 s42, s25, s10
	v_add_u32_e32 v5, 0, v242
	s_addc_u32 s43, s28, s11
	v_readfirstlane_b32 s2, v5
	v_add_u32_e32 v6, 0x4000, v5
	s_add_u32 s52, s22, s10
	v_mov_b32_e32 v4, v241
	s_mov_b32 m0, s2
	v_readfirstlane_b32 s2, v6
	v_add_u32_e32 v6, 0, v244
	s_addc_u32 s53, s23, s11
	v_add_u32_e32 v7, 0x4000, v6
	global_load_lds_dwordx4 v4, s[42:43]
	s_mov_b32 m0, s2
	v_readfirstlane_b32 s2, v6
	global_load_lds_dwordx4 v4, s[52:53]
	v_mov_b32_e32 v4, v243
	s_mov_b32 m0, s2
	v_readfirstlane_b32 s2, v7
	v_add_u32_e32 v7, 0x8000, v5
	global_load_lds_dwordx4 v4, s[42:43]
	s_mov_b32 m0, s2
	s_or_b32 s2, s10, 0x80000
	s_add_u32 s42, s25, s2
	s_addc_u32 s43, s28, s11
	s_add_u32 s10, s22, s2
	v_readfirstlane_b32 s2, v7
	v_add_u32_e32 v5, 0xc000, v5
	global_load_lds_dwordx4 v4, s[52:53]
	v_mov_b32_e32 v4, v241
	s_mov_b32 m0, s2
	v_readfirstlane_b32 s2, v5
	v_add_u32_e32 v5, 0x8000, v6
	s_addc_u32 s11, s23, s11
	v_add_f32_e32 v2, v2, v3
	global_load_lds_dwordx4 v4, s[42:43]
	s_mov_b32 m0, s2
	v_readfirstlane_b32 s2, v5
	v_add_u32_e32 v5, 0xc000, v6
	global_load_lds_dwordx4 v4, s[10:11]
	v_mov_b32_e32 v4, v243
	s_mov_b32 m0, s2
	v_readfirstlane_b32 s2, v5
	s_waitcnt vmcnt(0)
	v_mul_f32_e32 v1, v1, v2
	global_load_lds_dwordx4 v4, s[42:43]
	s_mov_b32 m0, s2
	v_mul_f32_e32 v2, 0x4f800000, v1
	global_load_lds_dwordx4 v4, s[10:11]
	v_cmp_gt_f32_e32 vcc, s65, v1
	v_mov_b32_e32 v66, v0
	v_mov_b32_e32 v67, v0
	v_cndmask_b32_e32 v1, v1, v2, vcc
	v_sqrt_f32_e32 v2, v1
	v_mov_b32_e32 v80, v0
	v_mov_b32_e32 v81, v0
	v_mov_b32_e32 v68, v0
	v_add_u32_e32 v3, -1, v2
	v_fma_f32 v4, -v3, v2, v1
	v_cmp_ge_f32_e64 s[42:43], 0, v4
	v_add_u32_e32 v4, 1, v2
	v_mov_b32_e32 v69, v0
	v_cndmask_b32_e64 v3, v2, v3, s[42:43]
	v_fma_f32 v2, -v4, v2, v1
	v_cmp_lt_f32_e64 s[42:43], 0, v2
	v_mov_b32_e32 v70, v0
	v_mov_b32_e32 v71, v0
	v_cndmask_b32_e64 v2, v3, v4, s[42:43]
	v_mul_f32_e32 v3, 0x37800000, v2
	v_cndmask_b32_e32 v2, v2, v3, vcc
	v_cmp_class_f32_e32 vcc, v1, v249
	v_mov_b32_e32 v72, v0
	v_mov_b32_e32 v73, v0
	v_cndmask_b32_e32 v1, v2, v1, vcc
	v_fmamk_f32 v1, v1, 0x3f8020c5, v252
	v_xor_b32_e32 v1, 0x80000000, v1
	v_cvt_pk_bf16_f32 v1, v1, 0
	v_and_b32_e32 v1, 0xffff, v1
	v_cndmask_b32_e64 v202, 0, v1, s[40:41]
	v_mov_b32_e32 v1, v0
	v_mov_b32_e32 v74, v0
	v_mov_b32_e32 v75, v0
	v_mov_b32_e32 v76, v0
	v_mov_b32_e32 v77, v0
	v_mov_b32_e32 v78, v0
	v_mov_b32_e32 v79, v0
	v_mov_b64_e32 v[96:97], v[80:81]
	v_mov_b64_e32 v[112:113], v[80:81]
	v_mov_b64_e32 v[128:129], v[80:81]
	v_mov_b64_e32 v[50:51], v[66:67]
	v_mov_b64_e32 v[34:35], v[66:67]
	v_mov_b64_e32 v[18:19], v[66:67]
	v_mov_b64_e32 v[2:3], v[66:67]
	s_mov_b32 s42, 0
	v_mov_b32_e32 v199, v0
	v_mov_b32_e32 v200, v0
	v_mov_b32_e32 v201, v0
	v_mov_b32_e32 v203, v0
	v_mov_b32_e32 v204, v0
	v_mov_b32_e32 v205, v0
	s_mov_b32 s37, 2
	v_mov_b64_e32 v[94:95], v[78:79]
	v_mov_b64_e32 v[92:93], v[76:77]
	v_mov_b64_e32 v[90:91], v[74:75]
	v_mov_b64_e32 v[88:89], v[72:73]
	v_mov_b64_e32 v[86:87], v[70:71]
	v_mov_b64_e32 v[84:85], v[68:69]
	v_mov_b64_e32 v[82:83], v[66:67]
	v_mov_b64_e32 v[110:111], v[78:79]
	v_mov_b64_e32 v[108:109], v[76:77]
	v_mov_b64_e32 v[106:107], v[74:75]
	v_mov_b64_e32 v[104:105], v[72:73]
	v_mov_b64_e32 v[102:103], v[70:71]
	v_mov_b64_e32 v[100:101], v[68:69]
	v_mov_b64_e32 v[98:99], v[66:67]
	v_mov_b64_e32 v[126:127], v[78:79]
	v_mov_b64_e32 v[124:125], v[76:77]
	v_mov_b64_e32 v[122:123], v[74:75]
	v_mov_b64_e32 v[120:121], v[72:73]
	v_mov_b64_e32 v[118:119], v[70:71]
	v_mov_b64_e32 v[116:117], v[68:69]
	v_mov_b64_e32 v[114:115], v[66:67]
	v_mov_b64_e32 v[52:53], v[68:69]
	v_mov_b64_e32 v[54:55], v[70:71]
	v_mov_b64_e32 v[56:57], v[72:73]
	v_mov_b64_e32 v[58:59], v[74:75]
	v_mov_b64_e32 v[60:61], v[76:77]
	v_mov_b64_e32 v[62:63], v[78:79]
	v_mov_b64_e32 v[64:65], v[80:81]
	v_mov_b64_e32 v[36:37], v[68:69]
	v_mov_b64_e32 v[38:39], v[70:71]
	v_mov_b64_e32 v[40:41], v[72:73]
	v_mov_b64_e32 v[42:43], v[74:75]
	v_mov_b64_e32 v[44:45], v[76:77]
	v_mov_b64_e32 v[46:47], v[78:79]
	v_mov_b64_e32 v[48:49], v[80:81]
	v_mov_b64_e32 v[20:21], v[68:69]
	v_mov_b64_e32 v[22:23], v[70:71]
	v_mov_b64_e32 v[24:25], v[72:73]
	v_mov_b64_e32 v[26:27], v[74:75]
	v_mov_b64_e32 v[28:29], v[76:77]
	v_mov_b64_e32 v[30:31], v[78:79]
	v_mov_b64_e32 v[32:33], v[80:81]
	v_mov_b64_e32 v[4:5], v[68:69]
	v_mov_b64_e32 v[6:7], v[70:71]
	v_mov_b64_e32 v[8:9], v[72:73]
	v_mov_b64_e32 v[10:11], v[74:75]
	v_mov_b64_e32 v[12:13], v[76:77]
	v_mov_b64_e32 v[14:15], v[78:79]
	v_mov_b64_e32 v[16:17], v[80:81]
	s_mov_b32 s29, 0
	v_mov_b64_e32 v[212:213], v[0:1]
	v_max_u32_e32 v130, v198, v202
	v_cmp_gt_u32_e32 vcc, 0xc270, v130
	s_nop 3
	s_cmp_eq_u64 vcc, exec
	s_cbranch_scc1 .Lfa_entry
	s_mov_b32 s34, s42
	s_cmpk_eq_i32 s29, 0x7f
	s_mov_b64 s[42:43], -1
	s_cbranch_scc1 .LBB0_43
	s_branch .LBB0_42
.LBB0_41:
	s_add_i32 s37, s42, 2
	s_and_b32 s37, s37, 3
	s_mov_b32 s34, s42
	s_cmpk_eq_i32 s29, 0x7f
	s_mov_b64 s[42:43], -1
	s_cbranch_scc1 .LBB0_43

; __device__ __forceinline__ void diff_attn_phase(const Params& p, LAS unsigned char* lds) {
;     ...
;         for (int ch = 0; ch < NCH; ++ch) {
;             if (ch + 1 < NCH) asm volatile("s_waitcnt vmcnt(4)" ::: "memory"); else asm volatile("s_waitcnt vmcnt(0)" ::: "memory");
;             __builtin_amdgcn_s_barrier(); asm volatile("" ::: "memory");
;             if (ch + 2 < NCH) issue(ch + 2, s_nn);
;             const LAS unsigned char* Ksb = lds + s_cur * STG; const LAS unsigned char* Vsb = Ksb + 16384;
;             s_nn = s_cur; s_cur = (s_cur == 2) ? 0 : s_cur + 1;
;     ...
;                 const LAS unsigned char* Ku = Ksb + u * 8192; const LAS unsigned char* Vu = Vsb + u * 8192;
;                 int kxl = kx, vb0l = vb0, vb1l = vb1; asm volatile("" : "+v"(kxl), "+v"(vb0l), "+v"(vb1l));
;                 bf16x8 kf[4];
; #pragma unroll
;                 for (int ks = 0; ks < 4; ++ks) kf[ks] = *(const LAS bf16x8*)(Ku + kbase + (kxl ^ (32 * ks)));
;                 bf16x8 P[2][2];
; #pragma unroll
;                 for (int r = 0; r < 2; ++r) {
;                     f32x16 S;
; #pragma unroll
;                     for (int i = 0; i < 16; ++i) S[i] = 0.f;
; #pragma unroll
;                     for (int ks = 0; ks < 4; ++ks) S = __builtin_amdgcn_mfma_f32_32x32x16_bf16(kf[ks], qf[r][ks], S, 0, 0, 0);
;                     S = __builtin_amdgcn_mfma_f32_32x32x16_bf16(kone, qm[r], S, 0, 0, 0);
; #pragma unroll
;                     for (int i = 0; i < 16; ++i) S[i] = __builtin_amdgcn_exp2f(S[i]);
;                     l[r] += sum16(S);
;                     P[r][0] = pack8(S, 0); P[r][1] = pack8(S, 8);
;                 }
; #pragma unroll
;                 for (int t = 0; t < 4; ++t) {
;                     const LAS unsigned char* a0 = Vu + (vb0l ^ (64 * t)); const LAS unsigned char* a1 = Vu + (vb1l ^ (64 * t));
;                     const bf16x8 v0 = tr_pair(a0, a1), v1 = tr_pair(a0 + 4096, a1 + 4096);
;                     O[0][t] = __builtin_amdgcn_mfma_f32_32x32x16_bf16(v0, P[0][0], O[0][t], 0, 0, 0);
;                     O[1][t] = __builtin_amdgcn_mfma_f32_32x32x16_bf16(v0, P[1][0], O[1][t], 0, 0, 0);
;                     O[0][t] = __builtin_amdgcn_mfma_f32_32x32x16_bf16(v1, P[0][1], O[0][t], 0, 0, 0);
;                     O[1][t] = __builtin_amdgcn_mfma_f32_32x32x16_bf16(v1, P[1][1], O[1][t], 0, 0, 0);
;                 }
.LBB0_48:
	v_mov_b32_e32 v208, v247
	v_mov_b32_e32 v209, v246
	v_mov_b32_e32 v210, v248
	v_add_u32_e32 v211, s47, v1
	s_movk_i32 s2, 0x60
	v_add_u32_e32 v130, v211, v209
	ds_read_b128 v[130:133], v130
	v_xad_u32 v214, v209, 32, v211
	ds_read_b128 v[214:217], v214
	v_xad_u32 v218, v209, 64, v211
	s_waitcnt lgkmcnt(0)
	v_mfma_f32_32x32x16_bf16 v[146:161], v[130:133], v[166:169], 0
	v_xad_u32 v209, v209, s2, v211
	s_add_i32 s47, s37, s47
	v_add_u32_e32 v226, s47, v208
	v_add_u32_e32 v228, s47, v210
	v_xad_u32 v237, v208, 64, s47
	v_xad_u32 v250, v210, 64, s47
	v_xor_b32_e32 v211, 0x80, v210
	v_mfma_f32_32x32x16_bf16 v[130:145], v[130:133], v[182:185], 0
	v_add_u32_e32 v238, s47, v211
	v_mfma_f32_32x32x16_bf16 v[146:161], v[214:217], v[170:173], v[146:161]
	v_mfma_f32_32x32x16_bf16 v[130:145], v[214:217], v[186:189], v[130:145]
	ds_read_b128 v[214:217], v218
	s_waitcnt lgkmcnt(0)
	v_mfma_f32_32x32x16_bf16 v[146:161], v[214:217], v[174:177], v[146:161]
	v_mfma_f32_32x32x16_bf16 v[130:145], v[214:217], v[190:193], v[130:145]
	ds_read_b128 v[214:217], v209
	s_nop 0
	ds_read_b64_tr_b16 v[222:223], v226 offset:16384
	ds_read_b64_tr_b16 v[224:225], v228 offset:16384
	v_xor_b32_e32 v209, 0x80, v208
	v_add_u32_e32 v251, s47, v209
	v_xor_b32_e32 v208, 0xc0, v208
	v_xor_b32_e32 v209, 0xc0, v210
	v_add_u32_e32 v239, s47, v208
	s_waitcnt lgkmcnt(2)
	v_mfma_f32_32x32x16_bf16 v[146:161], v[214:217], v[178:181], v[146:161]
	v_add_u32_e32 v234, s47, v209
	s_movk_i32 s47, 0x2000
	v_mfma_f32_32x32x16_bf16 v[130:145], v[214:217], v[194:197], v[130:145]
	v_mfma_f32_32x32x16_bf16 v[146:161], v[162:165], v[198:201], v[146:161]
	v_mfma_f32_32x32x16_bf16 v[130:145], v[162:165], v[202:205], v[130:145]
	s_nop 10
	v_exp_f32_e32 v215, v146
	v_exp_f32_e32 v219, v147
	v_exp_f32_e32 v217, v148
	v_exp_f32_e32 v221, v149
	v_exp_f32_e32 v147, v150
	v_exp_f32_e32 v151, v151
	v_exp_f32_e32 v149, v152
	v_exp_f32_e32 v153, v153
	v_exp_f32_e32 v214, v130
	v_exp_f32_e32 v218, v131
	v_exp_f32_e32 v216, v132
	v_exp_f32_e32 v220, v133
	v_exp_f32_e32 v146, v134
	v_exp_f32_e32 v150, v135
	v_exp_f32_e32 v148, v136
	v_exp_f32_e32 v152, v137
	v_cvt_pk_bf16_f32 v130, v215, v219
	v_cvt_pk_bf16_f32 v131, v217, v221
	v_cvt_pk_bf16_f32 v132, v147, v151
	v_cvt_pk_bf16_f32 v133, v149, v153
	v_cvt_pk_bf16_f32 v134, v214, v218
	v_cvt_pk_bf16_f32 v135, v216, v220
	v_cvt_pk_bf16_f32 v136, v146, v150
	v_cvt_pk_bf16_f32 v137, v148, v152
	s_waitcnt lgkmcnt(0)
	v_mfma_f32_32x32x16_bf16 v[114:129], v[222:225], v[130:133], v[114:129]
	v_exp_f32_e32 v227, v157
	v_exp_f32_e32 v157, v158
	v_exp_f32_e32 v229, v159
	v_exp_f32_e32 v159, v160
	v_exp_f32_e32 v158, v144
	v_exp_f32_e32 v160, v145
	v_exp_f32_e32 v161, v161
	v_mfma_f32_32x32x16_bf16 v[50:65], v[222:225], v[134:137], v[50:65]
	ds_read_b64_tr_b16 v[222:223], v237 offset:16384
	ds_read_b64_tr_b16 v[224:225], v250 offset:16384
	s_waitcnt lgkmcnt(0)
	v_mfma_f32_32x32x16_bf16 v[98:113], v[222:225], v[130:133], v[98:113]
	v_mfma_f32_32x32x16_bf16 v[34:49], v[222:225], v[134:137], v[34:49]
	ds_read_b64_tr_b16 v[222:223], v251 offset:16384
	ds_read_b64_tr_b16 v[224:225], v238 offset:16384
	ds_read_b64_tr_b16 v[208:209], v239 offset:16384
	ds_read_b64_tr_b16 v[210:211], v234 offset:16384
	ds_read_b64_tr_b16 v[230:231], v226 offset:20480
	ds_read_b64_tr_b16 v[232:233], v228 offset:20480
	v_exp_f32_e32 v226, v141
	v_exp_f32_e32 v228, v143
	s_waitcnt lgkmcnt(4)
	v_mfma_f32_32x32x16_bf16 v[82:97], v[222:225], v[130:133], v[82:97]
	v_mfma_f32_32x32x16_bf16 v[18:33], v[222:225], v[134:137], v[18:33]
	v_exp_f32_e32 v225, v155
	v_exp_f32_e32 v155, v156
	v_exp_f32_e32 v156, v142
	v_cndmask_b32_e64 v142, 0, 1, s[42:43]
	v_exp_f32_e32 v223, v154
	v_exp_f32_e32 v222, v138
	v_exp_f32_e32 v224, v139
	s_waitcnt lgkmcnt(2)
	v_mfma_f32_32x32x16_bf16 v[66:81], v[208:211], v[130:133], v[66:81]
	v_exp_f32_e32 v154, v140
	ds_read_b64_tr_b16 v[138:139], v251 offset:20480
	ds_read_b64_tr_b16 v[140:141], v238 offset:20480
	v_cmp_ne_u32_e32 vcc, 1, v142
	ds_read_b64_tr_b16 v[142:143], v239 offset:20480
	ds_read_b64_tr_b16 v[144:145], v234 offset:20480
	v_cvt_pk_bf16_f32 v130, v222, v224
	v_mfma_f32_32x32x16_bf16 v[2:17], v[208:211], v[134:137], v[2:17]
	ds_read_b64_tr_b16 v[208:209], v237 offset:20480
	ds_read_b64_tr_b16 v[210:211], v250 offset:20480
	v_cvt_pk_bf16_f32 v134, v223, v225
	v_cvt_pk_bf16_f32 v135, v155, v227
	v_cvt_pk_bf16_f32 v136, v157, v229
	v_cvt_pk_bf16_f32 v137, v159, v161
	v_cvt_pk_bf16_f32 v131, v154, v226
	v_cvt_pk_bf16_f32 v132, v156, v228
	v_cvt_pk_bf16_f32 v133, v158, v160
	s_waitcnt lgkmcnt(6)
	v_mfma_f32_32x32x16_bf16 v[114:129], v[230:233], v[134:137], v[114:129]
	s_mov_b64 s[42:43], 0
	s_and_b64 vcc, exec, vcc
	v_mfma_f32_32x32x16_bf16 v[50:65], v[230:233], v[130:133], v[50:65]
	s_waitcnt lgkmcnt(0)
	v_mfma_f32_32x32x16_bf16 v[98:113], v[208:211], v[134:137], v[98:113]
	v_mfma_f32_32x32x16_bf16 v[34:49], v[208:211], v[130:133], v[34:49]
	v_mfma_f32_32x32x16_bf16 v[82:97], v[138:141], v[134:137], v[82:97]
	v_mfma_f32_32x32x16_bf16 v[18:33], v[138:141], v[130:133], v[18:33]
	v_add_f32_e64 v138, v214, v218
	v_add_f32_e64 v139, v215, v219
	v_add_f32_e64 v140, v216, v220
	v_add_f32_e64 v141, v217, v221
	v_add_f32_e64 v138, v138, v140
	v_add_f32_e64 v139, v139, v141
	v_mfma_f32_32x32x16_bf16 v[66:81], v[142:145], v[134:137], v[66:81]
	v_add_f32_e64 v134, v146, v150
	v_add_f32_e64 v135, v147, v151
	v_add_f32_e64 v136, v148, v152
	v_add_f32_e64 v137, v149, v153
	v_add_f32_e64 v146, v222, v224
	v_add_f32_e64 v147, v223, v225
	v_pk_add_f32 v[148:149], v[154:155], v[226:227]
	v_pk_add_f32 v[150:151], v[156:157], v[228:229]
	v_pk_add_f32 v[152:153], v[158:159], v[160:161]
	v_mfma_f32_32x32x16_bf16 v[2:17], v[142:145], v[130:133], v[2:17]
	v_add_f32_e64 v130, v134, v136
	v_add_f32_e64 v131, v135, v137
	v_add_f32_e64 v132, v146, v148
	v_add_f32_e64 v133, v147, v149
	v_add_f32_e64 v134, v150, v152
	v_add_f32_e64 v135, v151, v153
	v_pk_add_f32 v[130:131], v[138:139], v[130:131]
	v_pk_add_f32 v[132:133], v[132:133], v[134:135]
	s_nop 0
	v_pk_add_f32 v[130:131], v[130:131], v[132:133]
	s_nop 0
	v_pk_add_f32 v[212:213], v[212:213], v[130:131]
	s_cbranch_vccz .LBB0_48
	s_add_i32 s29, s29, 1
	s_add_i32 s2, s34, 1
	s_and_b32 s42, s2, 3
	s_nop 0
	s_cmpk_lg_i32 s29, 0x80
	s_cbranch_scc1 .LBB0_41
	s_branch .Lad_epi
.Lfa_entry:
	s_mov_b32 s34, s42
	s_cmpk_eq_i32 s29, 0x7f
	s_mov_b64 s[42:43], -1
	s_cbranch_scc1 .Lfa_43
	s_branch .Lfa_42

; #define LAS __attribute__((address_space(3)))
; __device__ __forceinline__ void diff_attn_phase(const Params& p, LAS unsigned char* lds) {
;     ...
;                 const LAS unsigned char* Ku = Ksb + u * 8192; const LAS unsigned char* Vu = Vsb + u * 8192;
;                 int kxl = kx, vb0l = vb0, vb1l = vb1; asm volatile("" : "+v"(kxl), "+v"(vb0l), "+v"(vb1l));
;                 bf16x8 kf[4];
; #pragma unroll
;                 for (int ks = 0; ks < 4; ++ks) kf[ks] = *(const LAS bf16x8*)(Ku + kbase + (kxl ^ (32 * ks)));
;                 bf16x8 P[2][2];
; #pragma unroll
;                 for (int r = 0; r < 2; ++r) {
;                     f32x16 S;
; #pragma unroll
;                     for (int i = 0; i < 16; ++i) S[i] = 0.f;
; #pragma unroll
;                     for (int ks = 0; ks < 4; ++ks) S = __builtin_amdgcn_mfma_f32_32x32x16_bf16(kf[ks], qf[r][ks], S, 0, 0, 0);
;                     S = __builtin_amdgcn_mfma_f32_32x32x16_bf16(kone, qm[r], S, 0, 0, 0);
; #pragma unroll
;                     for (int i = 0; i < 16; ++i) S[i] = __builtin_amdgcn_exp2f(S[i]);
;                     l[r] += sum16(S);
;                     P[r][0] = pack8(S, 0); P[r][1] = pack8(S, 8);
;                 }
; #pragma unroll
;                 for (int t = 0; t < 4; ++t) {
;                     const LAS unsigned char* a0 = Vu + (vb0l ^ (64 * t)); const LAS unsigned char* a1 = Vu + (vb1l ^ (64 * t));
;                     const bf16x8 v0 = tr_pair(a0, a1), v1 = tr_pair(a0 + 4096, a1 + 4096);
;                     O[0][t] = __builtin_amdgcn_mfma_f32_32x32x16_bf16(v0, P[0][0], O[0][t], 0, 0, 0);
;                     O[1][t] = __builtin_amdgcn_mfma_f32_32x32x16_bf16(v0, P[1][0], O[1][t], 0, 0, 0);
;                     O[0][t] = __builtin_amdgcn_mfma_f32_32x32x16_bf16(v1, P[0][1], O[0][t], 0, 0, 0);
;                     O[1][t] = __builtin_amdgcn_mfma_f32_32x32x16_bf16(v1, P[1][1], O[1][t], 0, 0, 0);
;                 }
.Lfa_48:
	v_mov_b32_e32 v208, v247
	v_mov_b32_e32 v209, v246
	v_mov_b32_e32 v210, v248
	v_add_u32_e32 v211, s47, v1
	s_movk_i32 s2, 0x60
	v_add_u32_e32 v130, v211, v209
	ds_read_b128 v[130:133], v130
	v_xad_u32 v214, v209, 32, v211
	ds_read_b128 v[214:217], v214
	v_xad_u32 v218, v209, 64, v211
	s_waitcnt lgkmcnt(0)
	v_mfma_f32_32x32x16_bf16 v[146:161], v[130:133], v[166:169], 0
	v_xad_u32 v209, v209, s2, v211
	s_add_i32 s47, s37, s47
	v_add_u32_e32 v226, s47, v208
	v_add_u32_e32 v228, s47, v210
	v_xad_u32 v237, v208, 64, s47
	v_xad_u32 v250, v210, 64, s47
	v_xor_b32_e32 v211, 0x80, v210
	v_mfma_f32_32x32x16_bf16 v[130:145], v[130:133], v[182:185], 0
	v_add_u32_e32 v238, s47, v211
	v_mfma_f32_32x32x16_bf16 v[146:161], v[214:217], v[170:173], v[146:161]
	v_mfma_f32_32x32x16_bf16 v[130:145], v[214:217], v[186:189], v[130:145]
	ds_read_b128 v[214:217], v218
	s_waitcnt lgkmcnt(0)
	v_mfma_f32_32x32x16_bf16 v[146:161], v[214:217], v[174:177], v[146:161]
	v_mfma_f32_32x32x16_bf16 v[130:145], v[214:217], v[190:193], v[130:145]
	ds_read_b128 v[214:217], v209
	s_nop 0
	ds_read_b64_tr_b16 v[222:223], v226 offset:16384
	ds_read_b64_tr_b16 v[224:225], v228 offset:16384
	v_xor_b32_e32 v209, 0x80, v208
	v_add_u32_e32 v251, s47, v209
	v_xor_b32_e32 v208, 0xc0, v208
	v_xor_b32_e32 v209, 0xc0, v210
	v_add_u32_e32 v239, s47, v208
	s_waitcnt lgkmcnt(2)
	v_mfma_f32_32x32x16_bf16 v[146:161], v[214:217], v[178:181], v[146:161]
	v_add_u32_e32 v234, s47, v209
	s_movk_i32 s47, 0x2000
	v_mfma_f32_32x32x16_bf16 v[130:145], v[214:217], v[194:197], v[130:145]
	s_nop 11
	v_exp_f32_e32 v215, v146
	v_exp_f32_e32 v219, v147
	v_exp_f32_e32 v217, v148
	v_exp_f32_e32 v221, v149
	v_exp_f32_e32 v147, v150
	v_exp_f32_e32 v151, v151
	v_exp_f32_e32 v149, v152
	v_exp_f32_e32 v153, v153
	v_exp_f32_e32 v214, v130
	v_exp_f32_e32 v218, v131
	v_exp_f32_e32 v216, v132
	v_exp_f32_e32 v220, v133
	v_exp_f32_e32 v146, v134
	v_exp_f32_e32 v150, v135
	v_exp_f32_e32 v148, v136
	v_exp_f32_e32 v152, v137
	v_cvt_pk_bf16_f32 v130, v215, v219
	v_cvt_pk_bf16_f32 v131, v217, v221
	v_cvt_pk_bf16_f32 v132, v147, v151
	v_cvt_pk_bf16_f32 v133, v149, v153
	v_cvt_pk_bf16_f32 v134, v214, v218
	v_cvt_pk_bf16_f32 v135, v216, v220
	v_cvt_pk_bf16_f32 v136, v146, v150
	v_cvt_pk_bf16_f32 v137, v148, v152
	s_waitcnt lgkmcnt(0)
	v_mfma_f32_32x32x16_bf16 v[114:129], v[222:225], v[130:133], v[114:129]
	v_exp_f32_e32 v227, v157
	v_exp_f32_e32 v157, v158
	v_exp_f32_e32 v229, v159
	v_exp_f32_e32 v159, v160
	v_exp_f32_e32 v158, v144
	v_exp_f32_e32 v160, v145
	v_exp_f32_e32 v161, v161
	v_mfma_f32_32x32x16_bf16 v[50:65], v[222:225], v[134:137], v[50:65]
	ds_read_b64_tr_b16 v[222:223], v237 offset:16384
	ds_read_b64_tr_b16 v[224:225], v250 offset:16384
	s_waitcnt lgkmcnt(0)
	v_mfma_f32_32x32x16_bf16 v[98:113], v[222:225], v[130:133], v[98:113]
	v_mfma_f32_32x32x16_bf16 v[34:49], v[222:225], v[134:137], v[34:49]
	ds_read_b64_tr_b16 v[222:223], v251 offset:16384
	ds_read_b64_tr_b16 v[224:225], v238 offset:16384
	ds_read_b64_tr_b16 v[208:209], v239 offset:16384
	ds_read_b64_tr_b16 v[210:211], v234 offset:16384
	ds_read_b64_tr_b16 v[230:231], v226 offset:20480
	ds_read_b64_tr_b16 v[232:233], v228 offset:20480
	v_exp_f32_e32 v226, v141
	v_exp_f32_e32 v228, v143
	s_waitcnt lgkmcnt(4)
	v_mfma_f32_32x32x16_bf16 v[82:97], v[222:225], v[130:133], v[82:97]
	v_mfma_f32_32x32x16_bf16 v[18:33], v[222:225], v[134:137], v[18:33]
	v_exp_f32_e32 v225, v155
	v_exp_f32_e32 v155, v156
	v_exp_f32_e32 v156, v142
	v_cndmask_b32_e64 v142, 0, 1, s[42:43]
	v_exp_f32_e32 v223, v154
	v_exp_f32_e32 v222, v138
	v_exp_f32_e32 v224, v139
	s_waitcnt lgkmcnt(2)
	v_mfma_f32_32x32x16_bf16 v[66:81], v[208:211], v[130:133], v[66:81]
	v_exp_f32_e32 v154, v140
	ds_read_b64_tr_b16 v[138:139], v251 offset:20480
	ds_read_b64_tr_b16 v[140:141], v238 offset:20480
	v_cmp_ne_u32_e32 vcc, 1, v142
	ds_read_b64_tr_b16 v[142:143], v239 offset:20480
	ds_read_b64_tr_b16 v[144:145], v234 offset:20480
	v_cvt_pk_bf16_f32 v130, v222, v224
	v_mfma_f32_32x32x16_bf16 v[2:17], v[208:211], v[134:137], v[2:17]
	ds_read_b64_tr_b16 v[208:209], v237 offset:20480
	ds_read_b64_tr_b16 v[210:211], v250 offset:20480
	v_cvt_pk_bf16_f32 v134, v223, v225
	v_cvt_pk_bf16_f32 v135, v155, v227
	v_cvt_pk_bf16_f32 v136, v157, v229
	v_cvt_pk_bf16_f32 v137, v159, v161
	v_cvt_pk_bf16_f32 v131, v154, v226
	v_cvt_pk_bf16_f32 v132, v156, v228
	v_cvt_pk_bf16_f32 v133, v158, v160
	s_waitcnt lgkmcnt(6)
	v_mfma_f32_32x32x16_bf16 v[114:129], v[230:233], v[134:137], v[114:129]
	s_mov_b64 s[42:43], 0
	s_and_b64 vcc, exec, vcc
	v_mfma_f32_32x32x16_bf16 v[50:65], v[230:233], v[130:133], v[50:65]
	s_waitcnt lgkmcnt(0)
	v_mfma_f32_32x32x16_bf16 v[98:113], v[208:211], v[134:137], v[98:113]
	v_mfma_f32_32x32x16_bf16 v[34:49], v[208:211], v[130:133], v[34:49]
	v_mfma_f32_32x32x16_bf16 v[82:97], v[138:141], v[134:137], v[82:97]
	v_mfma_f32_32x32x16_bf16 v[18:33], v[138:141], v[130:133], v[18:33]
	v_add_f32_e64 v138, v214, v218
	v_add_f32_e64 v139, v215, v219
	v_add_f32_e64 v140, v216, v220
	v_add_f32_e64 v141, v217, v221
	v_add_f32_e64 v138, v138, v140
	v_add_f32_e64 v139, v139, v141
	v_mfma_f32_32x32x16_bf16 v[66:81], v[142:145], v[134:137], v[66:81]
	v_add_f32_e64 v134, v146, v150
	v_add_f32_e64 v135, v147, v151
	v_add_f32_e64 v136, v148, v152
	v_add_f32_e64 v137, v149, v153
	v_add_f32_e64 v146, v222, v224
	v_add_f32_e64 v147, v223, v225
	v_pk_add_f32 v[148:149], v[154:155], v[226:227]
	v_pk_add_f32 v[150:151], v[156:157], v[228:229]
	v_pk_add_f32 v[152:153], v[158:159], v[160:161]
	v_mfma_f32_32x32x16_bf16 v[2:17], v[142:145], v[130:133], v[2:17]
	v_add_f32_e64 v130, v134, v136
	v_add_f32_e64 v131, v135, v137
	v_add_f32_e64 v132, v146, v148
	v_add_f32_e64 v133, v147, v149
	v_add_f32_e64 v134, v150, v152
	v_add_f32_e64 v135, v151, v153
	v_pk_add_f32 v[130:131], v[138:139], v[130:131]
	v_pk_add_f32 v[132:133], v[132:133], v[134:135]
	s_nop 0
	v_pk_add_f32 v[130:131], v[130:131], v[132:133]
	s_nop 0
	v_pk_add_f32 v[212:213], v[212:213], v[130:131]
	s_cbranch_vccz .Lfa_48
	s_add_i32 s29, s29, 1
	s_add_i32 s2, s34, 1
	s_and_b32 s42, s2, 3
	s_nop 0
	s_cmpk_lg_i32 s29, 0x80
	s_cbranch_scc1 .Lfa_41
; #define LAS __attribute__((address_space(3)))
; __device__ __forceinline__ float xsum32(float v) { const auto r = __builtin_amdgcn_permlane32_swap(__float_as_uint(v), __float_as_uint(v), false, false); return __uint_as_float(r[0]) + __uint_as_float(r[1]); }
; __device__ __forceinline__ void diff_attn_phase(const Params& p, LAS unsigned char* lds) {
;     ...
;         int lne = lane; asm volatile("" : "+v"(lne));
;         const int hhe = lne >> 5, qle = lne & 31;
;         float lam;
;         { const float* lv = p.diff_lambda; const float a = lv[lne] * lv[64 + lne], bb = lv[128 + lne] * lv[192 + lne]; const int xa = ((lne ^ 32) << 2); lam = __expf(wave_sum(a, xa)) - __expf(wave_sum(bb, xa)) + p.lam_init; }
; #pragma unroll
;         for (int r = 0; r < 2; ++r) {
;             __builtin_amdgcn_s_barrier(); asm volatile("" ::: "memory");
;             LAS float* ex = (LAS float*)lds + wq * 4096 + lne;
;             const float lt = xsum32(l[r]);
;             if (comp == 1) {
;                 const float sc = lam / lt;
; #pragma unroll
;                 for (int t = 0; t < 4; ++t)
; #pragma unroll
;                     for (int i = 0; i < 16; ++i) ex[(t * 16 + i) * 64] = O[r][t][i] * sc;
;             }
.Lad_epi:
	v_mov_b32_e32 v130, v240
	v_readlane_b32 s92, v254, 42
	v_readlane_b32 s93, v254, 43
	v_ashrrev_i32_e32 v131, 31, v130
	s_load_dword s2, s[0:1], 0x220
	v_lshl_add_u64 v[132:133], v[130:131], 2, s[92:93]
	global_load_dword v1, v[132:133], off
	global_load_dword v131, v[132:133], off offset:256
	global_load_dword v134, v[132:133], off offset:512
	s_nop 0
	global_load_dword v132, v[132:133], off offset:768
	s_barrier
	s_and_b64 vcc, exec, s[44:45]
	v_readlane_b32 s94, v254, 44
	v_readlane_b32 s95, v254, 45
	s_waitcnt vmcnt(2)
	v_mul_f32_e32 v133, v1, v131
	ds_swizzle_b32 v133, v133 offset:swizzle(SWAP,1)
	s_waitcnt vmcnt(0)
	v_mul_f32_e32 v135, v134, v132
	ds_swizzle_b32 v135, v135 offset:swizzle(SWAP,1)
	s_waitcnt lgkmcnt(0)
	v_fmac_f32_e32 v133, v1, v131
	ds_swizzle_b32 v1, v133 offset:swizzle(SWAP,2)
	v_fmac_f32_e32 v135, v134, v132
	ds_swizzle_b32 v131, v135 offset:swizzle(SWAP,2)
	v_mov_b32_e32 v134, v213
	s_nop 1
	v_permlane32_swap_b32_e32 v213, v134
	s_waitcnt lgkmcnt(1)
	v_add_f32_e32 v1, v133, v1
	s_waitcnt lgkmcnt(0)
	v_add_f32_e32 v131, v135, v131
	ds_swizzle_b32 v132, v1 offset:swizzle(SWAP,4)
	ds_swizzle_b32 v133, v131 offset:swizzle(SWAP,4)
	v_lshlrev_b32_e32 v135, 2, v130
	v_xor_b32_e32 v136, 0x80, v135
	s_waitcnt lgkmcnt(1)
	v_add_f32_e32 v1, v1, v132
	s_waitcnt lgkmcnt(0)
	v_add_f32_e32 v131, v131, v133
	ds_swizzle_b32 v132, v1 offset:swizzle(SWAP,8)
	ds_swizzle_b32 v133, v131 offset:swizzle(SWAP,8)
	s_waitcnt lgkmcnt(1)
	v_add_f32_e32 v1, v1, v132
	s_waitcnt lgkmcnt(0)
	v_add_f32_e32 v131, v131, v133
	ds_swizzle_b32 v132, v1 offset:swizzle(SWAP,16)
	ds_swizzle_b32 v133, v131 offset:swizzle(SWAP,16)
	s_waitcnt lgkmcnt(1)
	v_add_f32_e32 v1, v1, v132
	s_waitcnt lgkmcnt(0)
	v_add_f32_e32 v131, v131, v133
	ds_bpermute_b32 v133, v136, v1
	ds_bpermute_b32 v136, v136, v131
	v_add_f32_e32 v132, v213, v134
	s_waitcnt lgkmcnt(1)
	v_add_f32_e32 v1, v1, v133
	s_waitcnt lgkmcnt(0)
	v_add_f32_e32 v131, v131, v136
	v_mul_f32_e32 v1, 0x3fb8aa3b, v1
	v_mul_f32_e32 v131, 0x3fb8aa3b, v131
	v_exp_f32_e32 v133, v1
	v_exp_f32_e32 v131, v131
	v_add_u32_e32 v1, s56, v135
	v_sub_f32_e32 v131, v133, v131
	v_add_f32_e32 v205, s2, v131
	s_cbranch_vccz .LBB0_52
	v_div_scale_f32 v131, s[10:11], v132, v132, v205
	v_rcp_f32_e32 v133, v131
	v_div_scale_f32 v134, vcc, v205, v132, v205
	v_fma_f32 v135, -v131, v133, 1.0
	v_fmac_f32_e32 v133, v135, v133
	v_mul_f32_e32 v135, v134, v133
	v_fma_f32 v136, -v131, v135, v134
	v_fmac_f32_e32 v135, v136, v133
	v_fma_f32 v131, -v131, v135, v134
	v_div_fmas_f32 v131, v131, v133, v135
	v_div_fixup_f32 v131, v131, v132, v205
	v_mul_f32_e32 v133, v114, v131
	v_mul_f32_e32 v134, v115, v131
	ds_write2st64_b32 v1, v133, v134 offset1:1
	v_mul_f32_e32 v133, v116, v131
	v_mul_f32_e32 v134, v117, v131
	ds_write2st64_b32 v1, v133, v134 offset0:2 offset1:3
	v_mul_f32_e32 v133, v118, v131
	v_mul_f32_e32 v134, v119, v131
	ds_write2st64_b32 v1, v133, v134 offset0:4 offset1:5
	v_mul_f32_e32 v133, v120, v131
	v_mul_f32_e32 v134, v121, v131
	ds_write2st64_b32 v1, v133, v134 offset0:6 offset1:7
	v_mul_f32_e32 v133, v122, v131
	v_mul_f32_e32 v134, v123, v131
	ds_write2st64_b32 v1, v133, v134 offset0:8 offset1:9
	v_mul_f32_e32 v133, v124, v131
	v_mul_f32_e32 v134, v125, v131
	ds_write2st64_b32 v1, v133, v134 offset0:10 offset1:11
	v_mul_f32_e32 v133, v126, v131
	v_mul_f32_e32 v134, v127, v131
	ds_write2st64_b32 v1, v133, v134 offset0:12 offset1:13
	v_mul_f32_e32 v133, v128, v131
	v_mul_f32_e32 v134, v129, v131
	ds_write2st64_b32 v1, v133, v134 offset0:14 offset1:15
	v_mul_f32_e32 v133, v98, v131
	v_mul_f32_e32 v134, v99, v131
	ds_write2st64_b32 v1, v133, v134 offset0:16 offset1:17
	v_mul_f32_e32 v133, v100, v131
	v_mul_f32_e32 v134, v101, v131
	ds_write2st64_b32 v1, v133, v134 offset0:18 offset1:19
	v_mul_f32_e32 v133, v102, v131
	v_mul_f32_e32 v134, v103, v131
	ds_write2st64_b32 v1, v133, v134 offset0:20 offset1:21
	v_mul_f32_e32 v133, v104, v131
	v_mul_f32_e32 v134, v105, v131
	ds_write2st64_b32 v1, v133, v134 offset0:22 offset1:23
	v_mul_f32_e32 v133, v106, v131
	v_mul_f32_e32 v134, v107, v131
	ds_write2st64_b32 v1, v133, v134 offset0:24 offset1:25
	v_mul_f32_e32 v133, v108, v131
	v_mul_f32_e32 v134, v109, v131
	ds_write2st64_b32 v1, v133, v134 offset0:26 offset1:27
	v_mul_f32_e32 v133, v110, v131
	v_mul_f32_e32 v134, v111, v131
	ds_write2st64_b32 v1, v133, v134 offset0:28 offset1:29
	v_mul_f32_e32 v133, v112, v131
	v_mul_f32_e32 v134, v113, v131
	ds_write2st64_b32 v1, v133, v134 offset0:30 offset1:31
	v_mul_f32_e32 v133, v82, v131
	v_mul_f32_e32 v134, v83, v131
	ds_write2st64_b32 v1, v133, v134 offset0:32 offset1:33
	v_mul_f32_e32 v133, v84, v131
	v_mul_f32_e32 v134, v85, v131
	ds_write2st64_b32 v1, v133, v134 offset0:34 offset1:35
	v_mul_f32_e32 v133, v86, v131
	v_mul_f32_e32 v134, v87, v131
	ds_write2st64_b32 v1, v133, v134 offset0:36 offset1:37
	v_mul_f32_e32 v133, v88, v131
	v_mul_f32_e32 v134, v89, v131
	ds_write2st64_b32 v1, v133, v134 offset0:38 offset1:39
	v_mul_f32_e32 v133, v90, v131
	v_mul_f32_e32 v134, v91, v131
	ds_write2st64_b32 v1, v133, v134 offset0:40 offset1:41
	v_mul_f32_e32 v133, v92, v131
	v_mul_f32_e32 v134, v93, v131
	ds_write2st64_b32 v1, v133, v134 offset0:42 offset1:43
	v_mul_f32_e32 v133, v94, v131
	v_mul_f32_e32 v134, v95, v131
	ds_write2st64_b32 v1, v133, v134 offset0:44 offset1:45
	v_mul_f32_e32 v133, v96, v131
	v_mul_f32_e32 v134, v97, v131
	ds_write2st64_b32 v1, v133, v134 offset0:46 offset1:47
	v_mul_f32_e32 v133, v66, v131
	v_mul_f32_e32 v134, v67, v131
	ds_write2st64_b32 v1, v133, v134 offset0:48 offset1:49
	v_mul_f32_e32 v133, v68, v131
	v_mul_f32_e32 v134, v69, v131
	ds_write2st64_b32 v1, v133, v134 offset0:50 offset1:51
	v_mul_f32_e32 v133, v70, v131
	v_mul_f32_e32 v134, v71, v131
	ds_write2st64_b32 v1, v133, v134 offset0:52 offset1:53
	v_mul_f32_e32 v133, v72, v131
	v_mul_f32_e32 v134, v73, v131
	ds_write2st64_b32 v1, v133, v134 offset0:54 offset1:55
	v_mul_f32_e32 v133, v74, v131
	v_mul_f32_e32 v134, v75, v131
	ds_write2st64_b32 v1, v133, v134 offset0:56 offset1:57
	v_mul_f32_e32 v133, v76, v131
	v_mul_f32_e32 v134, v77, v131
	ds_write2st64_b32 v1, v133, v134 offset0:58 offset1:59
	v_mul_f32_e32 v133, v78, v131
	v_mul_f32_e32 v134, v79, v131
	ds_write2st64_b32 v1, v133, v134 offset0:60 offset1:61
	v_mul_f32_e32 v133, v80, v131
	v_mul_f32_e32 v131, v81, v131
	ds_write2st64_b32 v1, v133, v131 offset0:62 offset1:63
